# phase 2 token shift: the previous-row loads no longer wait for the independent loads in flight (4 waits per unit removed)
# speedup vs baseline: 1.0049x; 1.0045x over previous
; DI void ld_cur_prev8(const Params& p, int row, int col, int mode, int sb, float* cur, float* prev) {
;     const u16* proj = (const u16*)(p.ws + W_PROJ);
;     unpack8(*(const uint4*)(proj + (size_t)row * NC + col), cur);
;     if (mode == 0) unpack8(*(const uint4*)(proj + (size_t)(row - 1) * NC + col), prev);
;     else if (mode == 1) { for (int i = 0; i < 8; ++i) prev[i] = 0.f; }
;     else { const float* s = p.st_shift + (size_t)sb * 1664 + (col - C_R); const float4 a = *(const float4*)s, b = *(const float4*)(s + 4);
;         prev[0] = a.x; prev[1] = a.y; prev[2] = a.z; prev[3] = a.w; prev[4] = b.x; prev[5] = b.y; prev[6] = b.z; prev[7] = b.w; }
; }
.LBB0_213:
	s_andn2_saveexec_b64 s[8:9], s[8:9]
	s_cbranch_execz .LBB0_215
	v_lshl_add_u64 v[6:7], s[68:69], 0, v[58:59]
	v_lshl_add_u64 v[6:7], v[6:7], 0, v[70:71]
	global_load_dwordx4 v[6:9], v[6:7], off
	s_waitcnt vmcnt(0)
	v_lshlrev_b32_e32 v10, 16, v6
	v_and_b32_e32 v11, 0xffff0000, v6
	v_lshlrev_b32_e32 v12, 16, v7
	v_and_b32_e32 v13, 0xffff0000, v7
	v_lshlrev_b32_e32 v6, 16, v8
	v_and_b32_e32 v7, 0xffff0000, v8
	v_lshlrev_b32_e32 v8, 16, v9
	v_and_b32_e32 v9, 0xffff0000, v9

; DI void ld_cur_prev8(const Params& p, int row, int col, int mode, int sb, float* cur, float* prev) {
;     const u16* proj = (const u16*)(p.ws + W_PROJ);
;     unpack8(*(const uint4*)(proj + (size_t)row * NC + col), cur);
;     if (mode == 0) unpack8(*(const uint4*)(proj + (size_t)(row - 1) * NC + col), prev);
;     else if (mode == 1) { for (int i = 0; i < 8; ++i) prev[i] = 0.f; }
;     else { const float* s = p.st_shift + (size_t)sb * 1664 + (col - C_R); const float4 a = *(const float4*)s, b = *(const float4*)(s + 4);
;         prev[0] = a.x; prev[1] = a.y; prev[2] = a.z; prev[3] = a.w; prev[4] = b.x; prev[5] = b.y; prev[6] = b.z; prev[7] = b.w; }
; }
.LBB0_219:
	s_andn2_saveexec_b64 s[8:9], s[8:9]
	s_cbranch_execz .LBB0_221
	v_lshl_add_u64 v[14:15], s[68:69], 0, v[58:59]
	v_lshl_add_u64 v[14:15], v[14:15], 0, v[70:71]
	global_load_dwordx4 v[14:17], v[14:15], off
	s_waitcnt vmcnt(0)
	v_lshlrev_b32_e32 v30, 16, v14
	v_and_b32_e32 v31, 0xffff0000, v14
	v_lshlrev_b32_e32 v32, 16, v15
	v_and_b32_e32 v33, 0xffff0000, v15
	v_lshlrev_b32_e32 v14, 16, v16
	v_and_b32_e32 v15, 0xffff0000, v16
	v_lshlrev_b32_e32 v16, 16, v17
	v_and_b32_e32 v17, 0xffff0000, v17

; DI void ld_cur_prev8(const Params& p, int row, int col, int mode, int sb, float* cur, float* prev) {
;     const u16* proj = (const u16*)(p.ws + W_PROJ);
;     unpack8(*(const uint4*)(proj + (size_t)row * NC + col), cur);
;     if (mode == 0) unpack8(*(const uint4*)(proj + (size_t)(row - 1) * NC + col), prev);
;     else if (mode == 1) { for (int i = 0; i < 8; ++i) prev[i] = 0.f; }
;     else { const float* s = p.st_shift + (size_t)sb * 1664 + (col - C_R); const float4 a = *(const float4*)s, b = *(const float4*)(s + 4);
;         prev[0] = a.x; prev[1] = a.y; prev[2] = a.z; prev[3] = a.w; prev[4] = b.x; prev[5] = b.y; prev[6] = b.z; prev[7] = b.w; }
; }
.LBB0_227:
	s_or_saveexec_b64 s[4:5], s[4:5]
	v_lshl_add_u64 v[58:59], s[68:69], 0, v[58:59]
	s_xor_b64 exec, exec, s[4:5]
	s_cbranch_execz .LBB0_229
	v_lshl_add_u64 v[6:7], v[58:59], 0, v[70:71]
	global_load_dwordx4 v[6:9], v[6:7], off
	s_waitcnt vmcnt(0)
	v_lshlrev_b32_e32 v10, 16, v6
	v_and_b32_e32 v11, 0xffff0000, v6
	v_lshlrev_b32_e32 v12, 16, v7
	v_and_b32_e32 v13, 0xffff0000, v7
	v_lshlrev_b32_e32 v6, 16, v8
	v_and_b32_e32 v7, 0xffff0000, v8
	v_lshlrev_b32_e32 v8, 16, v9
	v_and_b32_e32 v9, 0xffff0000, v9

; DI void ld_cur_prev8(const Params& p, int row, int col, int mode, int sb, float* cur, float* prev) {
;     const u16* proj = (const u16*)(p.ws + W_PROJ);
;     unpack8(*(const uint4*)(proj + (size_t)row * NC + col), cur);
;     if (mode == 0) unpack8(*(const uint4*)(proj + (size_t)(row - 1) * NC + col), prev);
;     else if (mode == 1) { for (int i = 0; i < 8; ++i) prev[i] = 0.f; }
;     else { const float* s = p.st_shift + (size_t)sb * 1664 + (col - C_R); const float4 a = *(const float4*)s, b = *(const float4*)(s + 4);
;         prev[0] = a.x; prev[1] = a.y; prev[2] = a.z; prev[3] = a.w; prev[4] = b.x; prev[5] = b.y; prev[6] = b.z; prev[7] = b.w; }
; }
.LBB0_233:
	s_andn2_saveexec_b64 s[4:5], s[4:5]
	s_cbranch_execz .LBB0_235
	v_lshl_add_u64 v[14:15], v[58:59], 0, v[70:71]
	global_load_dwordx4 v[14:17], v[14:15], off
	s_waitcnt vmcnt(0)
	v_lshlrev_b32_e32 v30, 16, v14
	v_and_b32_e32 v31, 0xffff0000, v14
	v_lshlrev_b32_e32 v32, 16, v15
	v_and_b32_e32 v33, 0xffff0000, v15
	v_lshlrev_b32_e32 v14, 16, v16
	v_and_b32_e32 v15, 0xffff0000, v16
	v_lshlrev_b32_e32 v16, 16, v17
	v_and_b32_e32 v17, 0xffff0000, v17
